# wait-state hardening 2: v_cmp -> v_cndmask mask reads in the pooling preheader padded to the compiler's 2 states; no functional change
# baseline (speedup 1.0000x reference)
; __device__ __forceinline__ float bf_lo(unsigned w) { return __uint_as_float(w << 16); }
; __device__ __forceinline__ float bf_hi(unsigned w) { return __uint_as_float(w & 0xffff0000u); }
; __device__ __forceinline__ void phase_mixer(const Params& p, LAS unsigned char* lds, int l, bool with_ctx, int G, int tid, int wave, int lane, int rep_attn, int rep_pool) {
;     ...
;     const int grp = lane >> 4, lo = 1 << grp, hi = lo - 1;
; #pragma unroll 1
;     for (int rp = 0; rp < rep_pool; ++rp)
; #pragma unroll 1
;     for (int run = gw; run < nrun; run += NGW) {
;         const int tok0 = run * 16; const bool isl = tok0 < ML;
;         const int base = isl ? (tok0 & ~(SEQ - 1)) : (ML + ((tok0 - ML) & ~(CT - 1))), len = isl ? SEQ : CT, t0 = tok0 - base;
;         u32x4 w[31];
; #pragma unroll
;         for (int i = 0; i < 31; ++i) { const int tt = min(max(t0 - 8 + i, 0), len - 1); w[i] = *(const u32x4*)(PB + (size_t)(base + tt) * PBW + 8 * lane); }
; #pragma unroll
;         for (int o = 0; o < 16; ++o) {
;             const int t = t0 + o, st = max(t - lo, 0), en = min(t + hi + 1, len);
;             float acc[8];
; #pragma unroll
;             for (int e = 0; e < 8; ++e) acc[e] = 0.f;
; #pragma unroll
;             for (int i = 0; i < 16; ++i) { const int tt = t + i - 8; const float wt = (tt >= st && tt < en) ? 1.f : 0.f; const u32x4 ww = w[o + i];
;                 acc[0] += wt * bf_lo(ww.x); acc[1] += wt * bf_hi(ww.x); acc[2] += wt * bf_lo(ww.y); acc[3] += wt * bf_hi(ww.y);
;                 acc[4] += wt * bf_lo(ww.z); acc[5] += wt * bf_hi(ww.z); acc[6] += wt * bf_lo(ww.w); acc[7] += wt * bf_hi(ww.w); }
;             const float ic = 1.f / (float)(en - st);
;             const u32x4 sw = w[o + 8];
.LBB0_306:
	v_readlane_b32 s4, v254, 22
	s_add_i32 s6, s87, s4
	s_and_b64 s[4:5], s[36:37], exec
	s_movk_i32 s4, 0x880
	s_cselect_b32 s7, s4, 0x800
	s_cmp_ge_i32 s6, s7
	s_cbranch_scc1 .LBB0_309
	v_lshlrev_b32_e32 v156, 4, v168
	v_lshlrev_b32_e64 v167, v106, 1
	v_cmp_le_u32_e32 vcc, 2, v167
	s_nop 1
	v_cndmask_b32_e64 v228, 0, 1.0, vcc
	v_cmp_le_u32_e32 vcc, 4, v167
	s_nop 1
	v_cndmask_b32_e64 v230, 0, 1.0, vcc
	v_cmp_le_u32_e32 vcc, 8, v167
	s_nop 1
	v_cndmask_b32_e64 v232, 0, 1.0, vcc
	v_mov_b32_e32 v234, 1.0
	v_lshl_add_u64 v[124:125], s[0:1], 0, v[156:157]
	v_lshl_add_u64 v[126:127], s[26:27], 0, v[156:157]
